# memory K/V tiles remapped so each XCD produces the two batches it consumes in cross-attention; publish without L2 write-back
# speedup vs baseline: 1.0118x; 1.0076x over previous
; #define PG8_STAGE(bufoff, gbase, voff) do { _Pragma("unroll") for (int _i = 0; _i < 2; ++_i) \
;         __builtin_amdgcn_global_load_lds((const unsigned*)((const char*)(gbase) + (voff)[_i]), (PG8_LAS unsigned*)(lds + (bufoff) + ldsw + _i * 8192), 16, 0, 0); } while (0)
; #define PG8_BAR __builtin_amdgcn_s_barrier()
;     __host__ __device__ bool next(int i, Unit& u) const {
;         const long L = (long)i * G + c; if (L >= nwg) return false;
;         int wgid = (int)L; { const int q = nwg / NXCD, r = nwg % NXCD, xcd = wgid % NXCD, off = wgid / NXCD; wgid = (xcd < r ? xcd * (q + 1) : r * (q + 1) + (xcd - r) * q) + off; }
;         const int nig = WGM * nN, gid = wgid / nig, fm = gid * WGM, gsz = (nM - fm) < WGM ? (nM - fm) : WGM;
;         u.pm = fm + ((wgid % nig) % gsz); u.pn = (wgid % nig) / gsz; return true;
; template <class Epi, class Sched, bool ALIGN_EPI = false, bool SP2 = false>
; __device__ __forceinline__ void gemm_phase(PG8_LAS unsigned char* lds, const Gemm g, const Sched& S, const Epi& E, const int wv) {
;     ...
;     for (int i = 0; i < 2; ++i) { int R, C; stage_rc(tid * 16 + i * 8192, R, C); const int Rb = Epi::PERM ? ((R & ~31) + perm32(R & 31)) : R;
;         voffA[i] = (unsigned)(R * K + C) * 2u; voffB[i] = (unsigned)(Rb * K + C) * 2u; }
;     const size_t kstep = (size_t)(BK * 2);
;     const size_t hstep = (size_t)HALF * K * 2;
;     const size_t tstep = 2 * hstep;
;     const unsigned ldsw = (unsigned)wid * 1024u;
;     const int aoff = lds_byte(wr * 64 + fr, fq * 8), boff = lds_byte(wc * 32 + fr, fq * 8);
;     ...
;     Unit cur, nxt; int ui = 0;
;     if (!S.next(0, cur)) return;
;     f32x4 acc[2][2][4][2];
; #pragma unroll
;     for (int a = 0; a < 2; ++a)
; #pragma unroll
;         for (int b = 0; b < 2; ++b)
; #pragma unroll
;             for (int m = 0; m < 4; ++m)
; #pragma unroll
;                 for (int n = 0; n < 2; ++n) acc[a][b][m][n] = (f32x4){0.f, 0.f, 0.f, 0.f};
;     bf16x8 At[4][2], B0[2][2], B1[2][2];
;     const char* cA = (const char*)g.A + (size_t)cur.pm * tstep; const char* cB = (const char*)g.Bt + (size_t)cur.pn * tstep;
;     S.a_ready(cur);
;     if constexpr (SP2) {
;         PG8_STAGE(PG8_SB(0, 0), cB, voffB); PG8_STAGE(PG8_SB(0, 1), cB + hstep, voffB); PG8_STAGE(PG8_SA(0, 0), cA, voffA); PG8_STAGE(PG8_SA(0, 1), cA + hstep, voffA);
;         if (wr == 1) PG8_BAR;
.LBB0_254:
	s_cmp_lt_i32 s2, 64
	s_cselect_b64 s[12:13], -1, 0
	v_mov_b32_e32 v8, v212
	s_and_b64 vcc, exec, s[12:13]
	s_cbranch_vccz .LBB0_256
	s_lshl_b32 s14, s68, 3
	s_mul_i32 s15, s68, 9
	s_and_b64 s[8:9], s[26:27], exec
	s_cselect_b32 s8, s15, s14
	s_add_i32 s8, s8, s67
	s_ashr_i32 s9, s8, 31
	s_lshr_b32 s9, s9, 27
	s_add_i32 s9, s8, s9
	s_ashr_i32 s14, s9, 5
	s_and_b32 s9, s9, 0xffe0
	s_sub_i32 s8, s8, s9
	s_bfe_i32 s9, s8, 0x80000
	s_bfe_u32 s9, s9, 0x3000c
	s_add_i32 s9, s8, s9
	s_bfe_i32 s15, s9, 0x80000
	s_and_b32 s9, s9, 0xf8
	s_sub_i32 s8, s8, s9
	s_lshl_b32 s14, s14, 3
	s_sext_i32_i16 s15, s15
	s_sext_i32_i8 s8, s8
	s_add_i32 s40, s14, s8
	s_ashr_i32 s8, s15, 3
	s_cmp_lg_u32 s20, 0x100
	s_cbranch_scc1 .Lmkv_keep
	s_and_b32 s40, s2, 7
	s_lshl_b32 s40, s40, 1
	s_lshr_b32 s14, s2, 5
	s_add_i32 s40, s40, s14
	s_bfe_u32 s8, s2, 0x20003
.Lmkv_keep:
.LBB0_256:
	v_cndmask_b32_e64 v128, 0, 1, s[12:13]
	s_andn2_b64 vcc, exec, s[12:13]
	s_cbranch_vccnz .LBB0_340
	v_lshl_add_u32 v0, v8, 4, s64
	v_ashrrev_i32_e32 v1, 31, v0
	v_lshrrev_b32_e32 v1, 22, v1
	v_add_u32_e32 v1, v0, v1
	v_ashrrev_i32_e32 v9, 10, v1
	v_mul_i32_i24_e32 v1, 0x400, v9
	v_sub_u32_e32 v1, v0, v1
	v_lshrrev_b32_e32 v2, 4, v1
	v_bitop3_b32 v1, v2, v1, 32 bitop3:0x6c
	v_ashrrev_i32_e32 v3, 31, v1
	v_lshrrev_b32_e32 v3, 26, v3
	v_add_u32_e32 v3, v1, v3
	v_lshlrev_b32_e32 v2, 3, v9
	v_ashrrev_i32_e32 v10, 6, v3
	v_and_b32_e32 v3, 0xc0, v3
	v_and_b32_e32 v2, -16, v2
	v_sub_u32_e32 v1, v1, v3
	v_mov_b32_e32 v3, 1
	v_add_u32_e32 v2, v10, v2
	v_ashrrev_i16_sdwa v1, v3, sext(v1) dst_sel:DWORD dst_unused:UNUSED_PAD src0_sel:DWORD src1_sel:BYTE_0
	s_waitcnt vmcnt(0)
	v_lshlrev_b32_e32 v4, 5, v9
	v_bfe_i32 v11, v1, 0, 16
	v_lshlrev_b32_e32 v1, 1, v2
	v_lshrrev_b32_e32 v5, 2, v2
	v_and_b32_e32 v6, 3, v10
	s_mov_b32 s9, 0x1fffe0
	v_and_b32_e32 v4, 32, v4
	v_and_b32_e32 v1, 24, v1
	v_and_b32_e32 v5, 4, v5
	v_and_or_b32 v6, v2, s9, v6
	v_or3_b32 v1, v6, v5, v1
	v_add_lshl_u32 v4, v4, v11, 1
	v_add_u32_e32 v0, 0x2000, v0
	v_lshl_add_u32 v132, v1, 11, v4
	v_ashrrev_i32_e32 v1, 31, v0
	v_lshrrev_b32_e32 v1, 22, v1
	v_add_u32_e32 v1, v0, v1
	v_ashrrev_i32_e32 v12, 10, v1
	v_mul_i32_i24_e32 v1, 0x400, v12
	v_sub_u32_e32 v0, v0, v1
	v_lshrrev_b32_e32 v1, 4, v0
	v_bitop3_b32 v0, v1, v0, 32 bitop3:0x6c
	v_lshl_add_u32 v130, v2, 11, v4
	v_ashrrev_i32_e32 v2, 31, v0
	v_lshrrev_b32_e32 v2, 26, v2
	v_add_u32_e32 v2, v0, v2
	v_ashrrev_i32_e32 v13, 6, v2
	v_and_b32_e32 v2, 0xffc0, v2
	v_sub_u32_e32 v0, v0, v2
	v_lshrrev_b16_e32 v2, 7, v0
	v_lshlrev_b32_e32 v1, 3, v12
	v_and_b32_e32 v2, 1, v2
	s_add_u32 s48, s10, 0xe00000
	v_and_b32_e32 v1, -16, v1
	v_add_u16_e32 v0, v0, v2
	s_addc_u32 s49, s11, 0
	v_add_u32_e32 v1, v13, v1
	v_ashrrev_i16_sdwa v0, v3, sext(v0) dst_sel:DWORD dst_unused:UNUSED_PAD src0_sel:DWORD src1_sel:BYTE_0
	v_and_b32_e32 v3, 3, v13
	s_add_u32 s50, s10, 0x2200000
	v_and_or_b32 v3, v1, s9, v3
	s_addc_u32 s51, s11, 0
	s_ashr_i32 s41, s40, 31
	s_ashr_i32 s9, s8, 31
	s_lshl_b64 s[12:13], s[40:41], 19
	s_lshl_b64 s[14:15], s[8:9], 19
	s_add_u32 s44, s48, s14
	v_lshlrev_b32_e32 v4, 5, v12
	v_bfe_i32 v14, v0, 0, 16
	v_lshlrev_b32_e32 v0, 1, v1
	v_lshrrev_b32_e32 v2, 2, v1
	s_addc_u32 s45, s49, s15
	s_add_i32 s52, s64, 0
	v_and_b32_e32 v4, 32, v4
	v_and_b32_e32 v0, 24, v0
	v_and_b32_e32 v2, 4, v2
	s_add_i32 m0, s52, 0x10000
	v_or3_b32 v0, v3, v2, v0
	v_add_lshl_u32 v2, v4, v14, 1
	global_load_lds_dwordx4 v132, s[44:45]
	s_add_i32 m0, s52, 0x12000
	v_lshl_add_u32 v136, v0, 11, v2
	s_add_u32 s14, s44, 0x40000
	global_load_lds_dwordx4 v136, s[44:45]
	s_addc_u32 s15, s45, 0
	s_add_i32 m0, s52, 0x14000
	v_lshl_add_u32 v134, v1, 11, v2
	global_load_lds_dwordx4 v132, s[14:15]
	s_add_i32 m0, s52, 0x16000
	s_add_u32 s42, s50, s12
	s_addc_u32 s43, s51, s13
	s_add_i32 s53, s52, 0x2000
	global_load_lds_dwordx4 v136, s[14:15]
	s_mov_b32 m0, s52
	s_add_u32 s12, s42, 0x40000
	global_load_lds_dwordx4 v130, s[42:43]
	s_mov_b32 m0, s53
	s_addc_u32 s13, s43, 0
	s_add_i32 s54, s52, 0x4000
	global_load_lds_dwordx4 v134, s[42:43]
	s_mov_b32 m0, s54
	s_add_i32 s55, s52, 0x6000
	global_load_lds_dwordx4 v130, s[12:13]
	s_mov_b32 m0, s55
	v_mov_b32_e32 v139, 0
	global_load_lds_dwordx4 v134, s[12:13]
	v_mov_b32_e32 v133, v139
	v_mov_b32_e32 v137, v139
	v_mov_b32_e32 v131, v139
	v_mov_b32_e32 v135, v139
	v_lshl_add_u64 v[6:7], s[44:45], 0, v[132:133]
	s_mov_b32 s56, 0
	v_lshl_add_u64 v[4:5], s[44:45], 0, v[136:137]
	v_lshl_add_u64 v[2:3], s[42:43], 0, v[130:131]
	s_and_b64 vcc, exec, s[6:7]
	v_lshl_add_u64 v[0:1], s[42:43], 0, v[134:135]
	s_cbranch_vccnz .LBB0_259
	s_barrier

; __device__ __forceinline__ int hw_lane() { int l = (int)__builtin_amdgcn_mbcnt_hi(~0u, __builtin_amdgcn_mbcnt_lo(~0u, 0u)); asm volatile("" : "+v"(l)); return l; }
; __device__ __forceinline__ gptr_t opq_ptr(const void* p) { gptr_t g = (gptr_t)p; asm volatile("" : "+s"(g)); return g; }
; __global__ void __launch_bounds__(NTHR, 2) hybrid_fwd(Args args) {
;     ...
;           pg8::Unit u0_; int nmine = 0; for (int i = 0; S.next(i, u0_); ++i) ++nmine;
;           if (nmine > 0) { asm volatile("s_waitcnt vmcnt(0)" ::: "memory"); __syncthreads();
;             if (wave == 0 && hw_lane() == 0) { __builtin_amdgcn_fence(__ATOMIC_RELEASE, "agent"); asm volatile("s_waitcnt vmcnt(0)" ::: "memory");
;               __hip_atomic_fetch_add((unsigned*)opq_ptr(args.ws) + 64 * 10, (unsigned)nmine, __ATOMIC_RELAXED, __HIP_MEMORY_SCOPE_AGENT); } } }
.LBB0_343:
	v_add_u32_e32 v0, s14, v128
	v_cmp_ne_u32_e32 vcc, 0, v0
	s_cbranch_vccz .LBB0_349
	s_waitcnt vmcnt(0)
	s_and_b64 vcc, exec, s[4:5]
	s_waitcnt vmcnt(0)
	s_barrier
	s_cbranch_vccnz .LBB0_349
	v_mov_b32_e32 v1, v212
	s_nop 0
	v_cmp_eq_u32_e32 vcc, 0, v1
	s_and_saveexec_b64 s[8:9], vcc
	s_cbranch_execz .LBB0_348
	s_mov_b64 s[10:11], exec
	v_mbcnt_lo_u32_b32 v1, s10, 0
	s_cmp_eq_u32 s20, 0x100
	s_cbranch_scc1 .Lmkv_nowb
	buffer_wbl2 sc1
	s_waitcnt vmcnt(0)
.Lmkv_nowb:
	v_mbcnt_hi_u32_b32 v1, s11, v1
	v_cmp_eq_u32_e32 vcc, 0, v1
	s_mov_b64 s[12:13], s[18:19]
	s_and_b64 s[14:15], exec, vcc
	s_mov_b64 exec, s[14:15]
	s_cbranch_execz .LBB0_348
	s_bcnt1_i32_b64 s10, s[10:11]
	v_mul_lo_u32 v0, v0, s10
	v_mov_b32_e32 v1, 0
	global_atomic_add v1, v0, s[12:13] offset:2560
